# attention: waves 4-7 start each stage 640 cycles late (s_sleep 10) to stagger the two waves of each SIMD
# baseline (speedup 1.0000x reference)
.Lattn_pro_done:
	s_waitcnt lgkmcnt(0)
	s_barrier
	v_readfirstlane_b32 s32, v0
	s_nop 3
	s_lshr_b32 s32, s32, 8
	s_cmp_lg_u32 s19, 0
	s_cselect_b64 s[28:29], -1, 0
	s_cmp_eq_u32 s19, 0
	s_cbranch_scc1 .LBB0_685

.LBB0_685:
	s_cmp_eq_u32 s32, 0
	s_cbranch_scc1 .Lattn_noskew
	s_sleep 10
